# combined: PEER pass-1 row prefetch one batch ahead + scan column-phase batched LDS reads + GEMM tile start waits vmcnt(16) instead of draining epilogue stores
# baseline (speedup 1.0000x reference)
.LBB0_89:
	v_lshl_or_b32 v138, s62, 6, v200
	v_ashrrev_i32_e32 v139, 31, v138
	v_lshlrev_b64 v[0:1], 11, v[138:139]
	v_lshl_add_u64 v[0:1], v[72:73], 0, v[0:1]
	s_barrier
	global_load_dwordx4 v[8:11], v[0:1], off offset:16
	global_load_dwordx4 v[12:15], v[0:1], off
	v_lshlrev_b64 v[0:1], 9, v[138:139]
	v_lshl_or_b32 v0, v68, 2, v0
	v_or_b32_e32 v4, 0x100, v0
	v_mov_b32_e32 v5, v1
	v_lshl_add_u64 v[6:7], s[54:55], 0, v[4:5]
	v_lshl_add_u64 v[4:5], s[56:57], 0, v[4:5]
	v_lshl_add_u64 v[2:3], s[54:55], 0, v[0:1]
	v_lshl_add_u64 v[0:1], s[56:57], 0, v[0:1]
	global_load_dword v16, v[4:5], off
	global_load_dword v17, v[0:1], off
	global_load_dword v140, v[2:3], off
	global_load_dword v142, v[6:7], off
	s_mov_b64 s[34:35], 0
	v_or_b32_e32 v127, 15, v138
	s_waitcnt vmcnt(5)
	v_mov_b64_e32 v[0:1], v[8:9]
	s_waitcnt vmcnt(4)
	v_mov_b64_e32 v[4:5], v[12:13]
	v_mov_b64_e32 v[2:3], v[10:11]
	v_mov_b64_e32 v[6:7], v[14:15]
	s_waitcnt vmcnt(3)
	v_mov_b32_e32 v145, v16
	s_waitcnt vmcnt(2)
	v_mov_b32_e32 v131, v17
	s_waitcnt vmcnt(1)
	s_mov_b32 s0, 0
	s_nop 0
	v_readlane_b32 s20, v140, s0
	s_ashr_i32 s21, s20, 31
	s_lshl_b64 s[20:21], s[20:21], 10
	v_lshl_add_u64 v[246:247], v[74:75], 0, s[20:21]
	global_load_dwordx4 v[226:229], v[246:247], off
	s_add_i32 s0, s0, 1
	v_readlane_b32 s20, v140, s0
	s_ashr_i32 s21, s20, 31
	s_lshl_b64 s[20:21], s[20:21], 10
	v_lshl_add_u64 v[246:247], v[74:75], 0, s[20:21]
	global_load_dwordx4 v[230:233], v[246:247], off
	s_add_i32 s0, s0, 1
	v_readlane_b32 s20, v140, s0
	s_ashr_i32 s21, s20, 31
	s_lshl_b64 s[20:21], s[20:21], 10
	v_lshl_add_u64 v[246:247], v[74:75], 0, s[20:21]
	global_load_dwordx4 v[234:237], v[246:247], off
	s_add_i32 s0, s0, 1
	v_readlane_b32 s20, v140, s0
	s_ashr_i32 s21, s20, 31
	s_lshl_b64 s[20:21], s[20:21], 10
	v_lshl_add_u64 v[246:247], v[74:75], 0, s[20:21]
	global_load_dwordx4 v[238:241], v[246:247], off
	s_add_i32 s0, s0, 1
	v_readlane_b32 s20, v140, s0
	s_ashr_i32 s21, s20, 31
	s_lshl_b64 s[20:21], s[20:21], 10
	v_lshl_add_u64 v[246:247], v[74:75], 0, s[20:21]
	global_load_dwordx4 v[242:245], v[246:247], off
	s_add_i32 s0, s0, 1
	v_readlane_b32 s20, v140, s0
	s_ashr_i32 s21, s20, 31
	s_lshl_b64 s[20:21], s[20:21], 10
	v_lshl_add_u64 v[246:247], v[74:75], 0, s[20:21]
	global_load_dwordx4 v[184:187], v[246:247], off
	s_add_i32 s0, s0, 1
	v_readlane_b32 s20, v140, s0
	s_ashr_i32 s21, s20, 31
	s_lshl_b64 s[20:21], s[20:21], 10
	v_lshl_add_u64 v[246:247], v[74:75], 0, s[20:21]
	global_load_dwordx4 v[188:191], v[246:247], off
	s_add_i32 s0, s0, 1
	v_readlane_b32 s20, v140, s0
	s_ashr_i32 s21, s20, 31
	s_lshl_b64 s[20:21], s[20:21], 10
	v_lshl_add_u64 v[246:247], v[74:75], 0, s[20:21]
	global_load_dwordx4 v[192:195], v[246:247], off
	s_branch .LBB0_91

.LBB0_95:
	s_waitcnt vmcnt(0)
	v_mov_b64_e32 v[218:219], v[226:227]
	v_mov_b64_e32 v[220:221], v[228:229]
	v_mov_b64_e32 v[64:65], v[230:231]
	v_mov_b64_e32 v[66:67], v[232:233]
	v_mov_b64_e32 v[60:61], v[234:235]
	v_mov_b64_e32 v[62:63], v[236:237]
	v_mov_b64_e32 v[56:57], v[238:239]
	v_mov_b64_e32 v[58:59], v[240:241]
	v_mov_b64_e32 v[52:53], v[242:243]
	v_mov_b64_e32 v[54:55], v[244:245]
	v_mov_b64_e32 v[48:49], v[184:185]
	v_mov_b64_e32 v[50:51], v[186:187]
	v_mov_b64_e32 v[44:45], v[188:189]
	v_mov_b64_e32 v[46:47], v[190:191]
	v_mov_b64_e32 v[40:41], v[192:193]
	v_mov_b64_e32 v[42:43], v[194:195]
	s_add_i32 s0, s1, 16
	s_cmp_lt_u32 s0, 64
	s_cselect_b64 s[50:51], -1, 0
	v_cndmask_b32_e64 v248, v142, v140, s[50:51]
	s_cmp_lt_u32 s0, 0x80
	s_cselect_b64 s[50:51], -1, 0
	s_nop 1
	v_cndmask_b32_e64 v248, v143, v248, s[50:51]
	s_and_b32 s0, s0, 63
	s_nop 0
	v_readlane_b32 s20, v248, s0
	s_ashr_i32 s21, s20, 31
	s_lshl_b64 s[20:21], s[20:21], 10
	v_lshl_add_u64 v[246:247], v[74:75], 0, s[20:21]
	global_load_dwordx4 v[226:229], v[246:247], off
	s_add_i32 s0, s0, 1
	v_readlane_b32 s20, v248, s0
	s_ashr_i32 s21, s20, 31
	s_lshl_b64 s[20:21], s[20:21], 10
	v_lshl_add_u64 v[246:247], v[74:75], 0, s[20:21]
	global_load_dwordx4 v[230:233], v[246:247], off
	s_add_i32 s0, s0, 1
	v_readlane_b32 s20, v248, s0
	s_ashr_i32 s21, s20, 31
	s_lshl_b64 s[20:21], s[20:21], 10
	v_lshl_add_u64 v[246:247], v[74:75], 0, s[20:21]
	global_load_dwordx4 v[234:237], v[246:247], off
	s_add_i32 s0, s0, 1
	v_readlane_b32 s20, v248, s0
	s_ashr_i32 s21, s20, 31
	s_lshl_b64 s[20:21], s[20:21], 10
	v_lshl_add_u64 v[246:247], v[74:75], 0, s[20:21]
	global_load_dwordx4 v[238:241], v[246:247], off
	s_add_i32 s0, s0, 1
	v_readlane_b32 s20, v248, s0
	s_ashr_i32 s21, s20, 31
	s_lshl_b64 s[20:21], s[20:21], 10
	v_lshl_add_u64 v[246:247], v[74:75], 0, s[20:21]
	global_load_dwordx4 v[242:245], v[246:247], off
	s_add_i32 s0, s0, 1
	v_readlane_b32 s20, v248, s0
	s_ashr_i32 s21, s20, 31
	s_lshl_b64 s[20:21], s[20:21], 10
	v_lshl_add_u64 v[246:247], v[74:75], 0, s[20:21]
	global_load_dwordx4 v[184:187], v[246:247], off
	s_add_i32 s0, s0, 1
	v_readlane_b32 s20, v248, s0
	s_ashr_i32 s21, s20, 31
	s_lshl_b64 s[20:21], s[20:21], 10
	v_lshl_add_u64 v[246:247], v[74:75], 0, s[20:21]
	global_load_dwordx4 v[188:191], v[246:247], off
	s_add_i32 s0, s0, 1
	v_readlane_b32 s20, v248, s0
	s_ashr_i32 s21, s20, 31
	s_lshl_b64 s[20:21], s[20:21], 10
	v_lshl_add_u64 v[246:247], v[74:75], 0, s[20:21]
	global_load_dwordx4 v[192:195], v[246:247], off
	s_cmp_lt_u32 s1, 64
	s_cselect_b64 vcc, -1, 0
	v_cndmask_b32_e32 v10, v142, v140, vcc
	s_add_i32 s0, s1, 8
	v_readlane_b32 s20, v10, s0
	s_ashr_i32 s21, s20, 31
	s_lshl_b64 s[20:21], s[20:21], 10
	v_lshl_add_u64 v[8:9], v[74:75], 0, s[20:21]
	global_load_dwordx4 v[36:39], v[8:9], off
	s_add_i32 s0, s1, 9
	v_readlane_b32 s20, v10, s0
	s_ashr_i32 s21, s20, 31
	s_lshl_b64 s[20:21], s[20:21], 10
	v_lshl_add_u64 v[8:9], v[74:75], 0, s[20:21]
	global_load_dwordx4 v[32:35], v[8:9], off
	s_add_i32 s0, s1, 10
	v_readlane_b32 s20, v10, s0
	s_ashr_i32 s21, s20, 31
	s_lshl_b64 s[20:21], s[20:21], 10
	v_lshl_add_u64 v[8:9], v[74:75], 0, s[20:21]
	global_load_dwordx4 v[28:31], v[8:9], off
	s_add_i32 s0, s1, 11
	v_readlane_b32 s20, v10, s0
	s_ashr_i32 s21, s20, 31
	s_lshl_b64 s[20:21], s[20:21], 10
	v_lshl_add_u64 v[8:9], v[74:75], 0, s[20:21]
	global_load_dwordx4 v[24:27], v[8:9], off
	s_add_i32 s0, s1, 12
	v_readlane_b32 s20, v10, s0
	s_ashr_i32 s21, s20, 31
	s_lshl_b64 s[20:21], s[20:21], 10
	v_lshl_add_u64 v[8:9], v[74:75], 0, s[20:21]
	global_load_dwordx4 v[20:23], v[8:9], off
	s_add_i32 s0, s1, 13
	v_readlane_b32 s20, v10, s0
	s_ashr_i32 s21, s20, 31
	s_lshl_b64 s[20:21], s[20:21], 10
	v_lshl_add_u64 v[8:9], v[74:75], 0, s[20:21]
	global_load_dwordx4 v[16:19], v[8:9], off
	s_add_i32 s0, s1, 14
	v_readlane_b32 s20, v10, s0
	s_ashr_i32 s21, s20, 31
	s_lshl_b64 s[20:21], s[20:21], 10
	v_lshl_add_u64 v[8:9], v[74:75], 0, s[20:21]
	global_load_dwordx4 v[12:15], v[8:9], off
	s_add_i32 s0, s1, 15
	v_readlane_b32 s20, v10, s0
	s_ashr_i32 s21, s20, 31
	s_lshl_b64 s[20:21], s[20:21], 10
	v_lshl_add_u64 v[8:9], v[74:75], 0, s[20:21]
	global_load_dwordx4 v[8:11], v[8:9], off
	v_cvt_pk_f32_fp8_e32 v[222:223], v218
	s_nop 0
	v_cvt_pk_f32_fp8_sdwa v[224:225], v218 src0_sel:WORD_1
	s_nop 0
	v_pk_fma_f32 v[222:223], v[222:223], v[146:147], 0 op_sel_hi:[1,1,0]
	v_pk_fma_f32 v[222:223], v[224:225], v[150:151], v[222:223]
	v_cvt_pk_f32_fp8_e32 v[224:225], v219
	s_nop 0
	v_cvt_pk_f32_fp8_sdwa v[218:219], v219 src0_sel:WORD_1
	s_nop 0
	v_pk_fma_f32 v[222:223], v[224:225], v[154:155], v[222:223]
	v_cvt_pk_f32_fp8_sdwa v[224:225], v220 src0_sel:WORD_1
	s_nop 0
	v_pk_fma_f32 v[218:219], v[218:219], v[158:159], v[222:223]
	v_cvt_pk_f32_fp8_e32 v[222:223], v220
	s_nop 0
	v_pk_fma_f32 v[218:219], v[222:223], v[148:149], v[218:219]
	v_cvt_pk_f32_fp8_e32 v[222:223], v221
	s_nop 0
	v_cvt_pk_f32_fp8_sdwa v[220:221], v221 src0_sel:WORD_1
	s_nop 0
	v_pk_fma_f32 v[218:219], v[224:225], v[152:153], v[218:219]
	v_pk_fma_f32 v[218:219], v[222:223], v[156:157], v[218:219]
	v_pk_fma_f32 v[218:219], v[220:221], v[160:161], v[218:219]
	v_cvt_pk_f32_fp8_sdwa v[220:221], v64 src0_sel:WORD_1
	v_add_f32_e32 v217, v218, v219
	v_cvt_pk_f32_fp8_e32 v[218:219], v64
	s_and_b32 s1, s1, 48
	v_cndmask_b32_e32 v216, v141, v139, vcc
	v_cndmask_b32_e32 v215, v212, v211, vcc
	v_pk_fma_f32 v[218:219], v[218:219], v[146:147], 0 op_sel_hi:[1,1,0]
	s_nop 0
	v_pk_fma_f32 v[218:219], v[220:221], v[150:151], v[218:219]
	v_cvt_pk_f32_fp8_e32 v[220:221], v65
	v_cvt_pk_f32_fp8_sdwa v[64:65], v65 src0_sel:WORD_1
	v_pk_fma_f32 v[218:219], v[220:221], v[154:155], v[218:219]
	s_nop 0
	v_pk_fma_f32 v[64:65], v[64:65], v[158:159], v[218:219]
	v_cvt_pk_f32_fp8_e32 v[218:219], v66
	v_cvt_pk_f32_fp8_sdwa v[220:221], v66 src0_sel:WORD_1
	v_pk_fma_f32 v[64:65], v[218:219], v[148:149], v[64:65]
	v_cvt_pk_f32_fp8_e32 v[218:219], v67
	v_cvt_pk_f32_fp8_sdwa v[66:67], v67 src0_sel:WORD_1
	v_pk_fma_f32 v[64:65], v[220:221], v[152:153], v[64:65]
	s_nop 0
	v_pk_fma_f32 v[64:65], v[218:219], v[156:157], v[64:65]
	s_nop 0
	v_pk_fma_f32 v[64:65], v[66:67], v[160:161], v[64:65]
	v_cvt_pk_f32_fp8_sdwa v[66:67], v60 src0_sel:WORD_1
	v_add_f32_e32 v218, v64, v65
	v_cvt_pk_f32_fp8_e32 v[64:65], v60
	v_pk_fma_f32 v[64:65], v[64:65], v[146:147], 0 op_sel_hi:[1,1,0]
	s_nop 0
	v_pk_fma_f32 v[64:65], v[66:67], v[150:151], v[64:65]
	v_cvt_pk_f32_fp8_e32 v[66:67], v61
	v_cvt_pk_f32_fp8_sdwa v[60:61], v61 src0_sel:WORD_1
	v_pk_fma_f32 v[64:65], v[66:67], v[154:155], v[64:65]
	s_nop 0
	v_pk_fma_f32 v[60:61], v[60:61], v[158:159], v[64:65]
	v_cvt_pk_f32_fp8_e32 v[64:65], v62
	v_cvt_pk_f32_fp8_sdwa v[66:67], v62 src0_sel:WORD_1
	v_pk_fma_f32 v[60:61], v[64:65], v[148:149], v[60:61]
	v_cvt_pk_f32_fp8_e32 v[64:65], v63
	v_cvt_pk_f32_fp8_sdwa v[62:63], v63 src0_sel:WORD_1
	v_pk_fma_f32 v[60:61], v[66:67], v[152:153], v[60:61]
	s_nop 0
	v_pk_fma_f32 v[60:61], v[64:65], v[156:157], v[60:61]
	s_nop 0
	v_pk_fma_f32 v[60:61], v[62:63], v[160:161], v[60:61]
	v_cvt_pk_f32_fp8_sdwa v[62:63], v56 src0_sel:WORD_1
	v_add_f32_e32 v64, v60, v61
	v_cvt_pk_f32_fp8_e32 v[60:61], v56
	v_pk_fma_f32 v[60:61], v[60:61], v[146:147], 0 op_sel_hi:[1,1,0]
	s_nop 0
	v_pk_fma_f32 v[60:61], v[62:63], v[150:151], v[60:61]
	v_cvt_pk_f32_fp8_e32 v[62:63], v57
	v_cvt_pk_f32_fp8_sdwa v[56:57], v57 src0_sel:WORD_1
	v_pk_fma_f32 v[60:61], v[62:63], v[154:155], v[60:61]
	s_nop 0
	v_pk_fma_f32 v[56:57], v[56:57], v[158:159], v[60:61]
	v_cvt_pk_f32_fp8_e32 v[60:61], v58
	v_cvt_pk_f32_fp8_sdwa v[62:63], v58 src0_sel:WORD_1
	v_pk_fma_f32 v[56:57], v[60:61], v[148:149], v[56:57]
	v_cvt_pk_f32_fp8_e32 v[60:61], v59
	v_cvt_pk_f32_fp8_sdwa v[58:59], v59 src0_sel:WORD_1
	v_pk_fma_f32 v[56:57], v[62:63], v[152:153], v[56:57]
	s_nop 0
	v_pk_fma_f32 v[56:57], v[60:61], v[156:157], v[56:57]
	s_nop 0
	v_pk_fma_f32 v[56:57], v[58:59], v[160:161], v[56:57]
	v_cvt_pk_f32_fp8_sdwa v[58:59], v52 src0_sel:WORD_1
	v_add_f32_e32 v60, v56, v57
	v_cvt_pk_f32_fp8_e32 v[56:57], v52
	v_pk_fma_f32 v[56:57], v[56:57], v[146:147], 0 op_sel_hi:[1,1,0]
	s_nop 0
	v_pk_fma_f32 v[56:57], v[58:59], v[150:151], v[56:57]
	v_cvt_pk_f32_fp8_e32 v[58:59], v53
	v_cvt_pk_f32_fp8_sdwa v[52:53], v53 src0_sel:WORD_1
	v_pk_fma_f32 v[56:57], v[58:59], v[154:155], v[56:57]
	s_nop 0
	v_pk_fma_f32 v[52:53], v[52:53], v[158:159], v[56:57]
	v_cvt_pk_f32_fp8_e32 v[56:57], v54
	v_cvt_pk_f32_fp8_sdwa v[58:59], v54 src0_sel:WORD_1
	v_pk_fma_f32 v[52:53], v[56:57], v[148:149], v[52:53]
	v_cvt_pk_f32_fp8_e32 v[56:57], v55
	v_cvt_pk_f32_fp8_sdwa v[54:55], v55 src0_sel:WORD_1
	v_pk_fma_f32 v[52:53], v[58:59], v[152:153], v[52:53]
	s_nop 0
	v_pk_fma_f32 v[52:53], v[56:57], v[156:157], v[52:53]
	s_nop 0
	v_pk_fma_f32 v[52:53], v[54:55], v[160:161], v[52:53]
	v_cvt_pk_f32_fp8_sdwa v[54:55], v48 src0_sel:WORD_1
	v_add_f32_e32 v56, v52, v53
	v_cvt_pk_f32_fp8_e32 v[52:53], v48
	v_pk_fma_f32 v[52:53], v[52:53], v[146:147], 0 op_sel_hi:[1,1,0]
	s_nop 0
	v_pk_fma_f32 v[52:53], v[54:55], v[150:151], v[52:53]
	v_cvt_pk_f32_fp8_e32 v[54:55], v49
	v_cvt_pk_f32_fp8_sdwa v[48:49], v49 src0_sel:WORD_1
	v_pk_fma_f32 v[52:53], v[54:55], v[154:155], v[52:53]
	s_nop 0
	v_pk_fma_f32 v[48:49], v[48:49], v[158:159], v[52:53]
	v_cvt_pk_f32_fp8_e32 v[52:53], v50
	v_cvt_pk_f32_fp8_sdwa v[54:55], v50 src0_sel:WORD_1
	v_pk_fma_f32 v[48:49], v[52:53], v[148:149], v[48:49]
	v_cvt_pk_f32_fp8_e32 v[52:53], v51
	v_cvt_pk_f32_fp8_sdwa v[50:51], v51 src0_sel:WORD_1
	v_pk_fma_f32 v[48:49], v[54:55], v[152:153], v[48:49]
	s_nop 0
	v_pk_fma_f32 v[48:49], v[52:53], v[156:157], v[48:49]
	s_nop 0
	v_pk_fma_f32 v[48:49], v[50:51], v[160:161], v[48:49]
	v_cvt_pk_f32_fp8_sdwa v[50:51], v44 src0_sel:WORD_1
	v_add_f32_e32 v52, v48, v49
	v_cvt_pk_f32_fp8_e32 v[48:49], v44
	v_pk_fma_f32 v[48:49], v[48:49], v[146:147], 0 op_sel_hi:[1,1,0]
	s_nop 0
	v_pk_fma_f32 v[48:49], v[50:51], v[150:151], v[48:49]
	v_cvt_pk_f32_fp8_e32 v[50:51], v45
	v_cvt_pk_f32_fp8_sdwa v[44:45], v45 src0_sel:WORD_1
	v_pk_fma_f32 v[48:49], v[50:51], v[154:155], v[48:49]
	s_nop 0
	v_pk_fma_f32 v[44:45], v[44:45], v[158:159], v[48:49]
	v_cvt_pk_f32_fp8_e32 v[48:49], v46
	v_cvt_pk_f32_fp8_sdwa v[50:51], v46 src0_sel:WORD_1
	v_pk_fma_f32 v[44:45], v[48:49], v[148:149], v[44:45]
	v_cvt_pk_f32_fp8_e32 v[48:49], v47
	v_cvt_pk_f32_fp8_sdwa v[46:47], v47 src0_sel:WORD_1
	v_pk_fma_f32 v[44:45], v[50:51], v[152:153], v[44:45]
	s_nop 0
	v_pk_fma_f32 v[44:45], v[48:49], v[156:157], v[44:45]
	s_nop 0
	v_pk_fma_f32 v[44:45], v[46:47], v[160:161], v[44:45]
	v_cvt_pk_f32_fp8_sdwa v[46:47], v40 src0_sel:WORD_1
	v_add_f32_e32 v48, v44, v45
	v_cvt_pk_f32_fp8_e32 v[44:45], v40
	v_pk_fma_f32 v[44:45], v[44:45], v[146:147], 0 op_sel_hi:[1,1,0]
	s_nop 0
	v_pk_fma_f32 v[44:45], v[46:47], v[150:151], v[44:45]
	v_cvt_pk_f32_fp8_e32 v[46:47], v41
	v_cvt_pk_f32_fp8_sdwa v[40:41], v41 src0_sel:WORD_1
	v_pk_fma_f32 v[44:45], v[46:47], v[154:155], v[44:45]
	s_nop 0
	v_pk_fma_f32 v[40:41], v[40:41], v[158:159], v[44:45]
	v_cvt_pk_f32_fp8_e32 v[44:45], v42
	v_cvt_pk_f32_fp8_sdwa v[46:47], v42 src0_sel:WORD_1
	v_pk_fma_f32 v[40:41], v[44:45], v[148:149], v[40:41]
	v_cvt_pk_f32_fp8_e32 v[44:45], v43
	v_cvt_pk_f32_fp8_sdwa v[42:43], v43 src0_sel:WORD_1
	v_pk_fma_f32 v[40:41], v[46:47], v[152:153], v[40:41]
	s_nop 0
	v_pk_fma_f32 v[40:41], v[44:45], v[156:157], v[40:41]
	v_cndmask_b32_e64 v44, v64, v48, s[44:45]
	v_pk_fma_f32 v[40:41], v[42:43], v[160:161], v[40:41]
	v_cndmask_b32_e64 v42, v217, v56, s[44:45]
	ds_bpermute_b32 v42, v201, v42
	v_cndmask_b32_e64 v43, v218, v52, s[44:45]
	ds_bpermute_b32 v43, v201, v43
	ds_bpermute_b32 v44, v201, v44
	v_add_f32_e32 v40, v40, v41
	v_cndmask_b32_e64 v41, v56, v217, s[44:45]
	s_waitcnt lgkmcnt(2)
	v_add_f32_e32 v41, v41, v42
	v_cndmask_b32_e64 v42, v52, v218, s[44:45]
	s_waitcnt lgkmcnt(1)
	v_add_f32_e32 v42, v42, v43
	v_cndmask_b32_e64 v43, v48, v64, s[44:45]
	s_waitcnt lgkmcnt(0)
	v_add_f32_e32 v43, v43, v44
	v_cndmask_b32_e64 v44, v40, v60, s[44:45]
	v_cndmask_b32_e64 v40, v60, v40, s[44:45]
	ds_bpermute_b32 v40, v201, v40
	s_waitcnt lgkmcnt(0)
	v_add_f32_e32 v40, v44, v40
	v_cndmask_b32_e64 v44, v43, v41, s[46:47]
	v_cndmask_b32_e64 v41, v41, v43, s[46:47]
	v_cndmask_b32_e64 v43, v40, v42, s[46:47]
	v_cndmask_b32_e64 v40, v42, v40, s[46:47]
	ds_bpermute_b32 v41, v202, v41
	ds_bpermute_b32 v40, v202, v40
	s_waitcnt lgkmcnt(1)
	v_add_f32_e32 v41, v44, v41
	s_waitcnt lgkmcnt(0)
	v_add_f32_e32 v40, v43, v40
	v_cndmask_b32_e64 v42, v40, v41, s[48:49]
	v_cndmask_b32_e64 v40, v41, v40, s[48:49]
	ds_bpermute_b32 v40, v203, v40
	s_waitcnt lgkmcnt(0)
	v_add_f32_e32 v40, v42, v40
	ds_bpermute_b32 v41, v204, v40
	s_waitcnt lgkmcnt(0)
	v_add_f32_e32 v40, v40, v41
	ds_bpermute_b32 v41, v205, v40
	s_waitcnt lgkmcnt(0)
	v_add_f32_e32 v40, v40, v41
	ds_bpermute_b32 v41, v206, v40
	s_waitcnt lgkmcnt(0)
	v_add_f32_e32 v41, v40, v41
	v_or_b32_e32 v40, s1, v207
	v_lshlrev_b32_e32 v40, 2, v40
	ds_bpermute_b32 v42, v40, v216
	ds_bpermute_b32 v40, v40, v215
	s_waitcnt lgkmcnt(1)
	v_mul_f32_e32 v41, v41, v42
	v_mul_f32_e32 v42, 0x3f3504f3, v41
	v_cmp_nlt_f32_e64 s[20:21], |v42|, 1.0
	s_and_saveexec_b64 s[24:25], s[20:21]
	s_xor_b64 s[52:53], exec, s[24:25]
	s_cbranch_execz .LBB0_97
	v_fma_f32 v43, |v42|, s36, v181
	v_fma_f32 v43, |v42|, v43, s37
	v_fma_f32 v43, |v42|, v43, s27
	v_fma_f32 v43, |v42|, v43, s29
	v_fma_f32 v43, |v42|, v43, s22
	v_fma_f32 v43, |v42|, v43, s23
	v_fma_f32 v43, |v42|, v43, |v42|
	v_mul_f32_e32 v44, 0xbfb8aa3b, v43
	v_fma_f32 v45, v43, s96, -v44
	v_rndne_f32_e32 v46, v44
	v_fmac_f32_e32 v45, 0xb2a5705f, v43
	v_sub_f32_e32 v44, v44, v46
	v_add_f32_e32 v44, v44, v45
	v_cvt_i32_f32_e32 v45, v46
	v_exp_f32_e32 v44, v44
	v_cmp_nlt_f32_e64 s[50:51], s2, v43
	v_ldexp_f32 v44, v44, v45
	s_nop 0
	v_cndmask_b32_e64 v44, 0, v44, s[50:51]
	v_cmp_ngt_f32_e64 s[50:51], s3, v43
	s_nop 1
	v_cndmask_b32_e64 v43, v182, v44, s[50:51]
	v_sub_f32_e32 v43, 1.0, v43

.LBB0_103:
	s_waitcnt vmcnt(0)
	s_mov_b64 s[0:1], exec
	s_mov_b64 exec, -1
	v_mov_b32_e32 v184, 0x70
	v_mov_b32_e32 v185, 0xf0
	v_mov_b32_e32 v186, 0x48
	v_mov_b32_e32 v187, 0x60
	v_bfrev_b32_e32 v188, 32
	v_mov_b32_e32 v189, 0x3000
	v_mov_b32_e32 v190, 0x4800
	v_mov_b32_e32 v191, 0x8c0
	v_mov_b32_e32 v192, 0x41b17218
	v_mov_b32_e32 v193, 0xfffffc00
	v_mov_b32_e32 v194, 0x1000
	v_mov_b32_e32 v195, 0x800
	s_mov_b64 exec, s[0:1]
	s_mov_b32 s24, 0x8000
	s_movk_i32 s25, 0x1000

.LBB0_124:
	s_lshl_b32 s42, s42, 8
	s_lshl_b32 s44, s44, 8
	s_xor_b64 s[20:21], s[38:39], -1
	s_ashr_i32 s43, s42, 31
	s_ashr_i32 s45, s44, 31
	s_xor_b64 s[40:41], s[46:47], -1
	s_lshl_b64 s[38:39], s[42:43], 11
	s_lshl_b64 s[48:49], s[44:45], 11
	s_andn2_b64 vcc, exec, s[20:21]
	v_add_u32_e32 v205, 0x2000, v150
	v_add_u32_e32 v204, 0x4000, v150
	v_add_u32_e32 v203, 0x6000, v150
	v_add_u32_e32 v202, 0x8000, v150
	v_add_u32_e32 v201, 0xa000, v150
	v_add_u32_e32 v200, 0xc000, v150
	v_add_u32_e32 v199, 0xe000, v150
	s_cbranch_vccnz .LBB0_126
	s_add_u32 s20, s30, s38
	s_addc_u32 s21, s31, s39
	v_lshl_add_u64 v[0:1], s[20:21], 0, v[132:133]
	v_readfirstlane_b32 s20, v150
	s_mov_b32 m0, s20
	s_mov_b64 s[50:51], 0x20000
	v_readfirstlane_b32 s20, v205
	global_load_lds_dwordx4 v[0:1], off
	v_lshl_add_u64 v[2:3], v[0:1], 0, s[50:51]
	s_mov_b32 m0, s20
	s_mov_b64 s[58:59], 0x40000
	v_readfirstlane_b32 s20, v204
	s_add_u32 s24, s34, s48
	global_load_lds_dwordx4 v[2:3], off
	v_lshl_add_u64 v[2:3], v[0:1], 0, s[58:59]
	s_mov_b32 m0, s20
	s_mov_b64 s[60:61], 0x60000
	v_readfirstlane_b32 s20, v203
	s_addc_u32 s25, s35, s49
	global_load_lds_dwordx4 v[2:3], off
	v_lshl_add_u64 v[0:1], v[0:1], 0, s[60:61]
	s_mov_b32 m0, s20
	v_readfirstlane_b32 s20, v202
	global_load_lds_dwordx4 v[0:1], off
	v_lshl_add_u64 v[0:1], s[24:25], 0, v[132:133]
	s_mov_b32 m0, s20
	v_readfirstlane_b32 s20, v201
	global_load_lds_dwordx4 v[0:1], off
	v_lshl_add_u64 v[2:3], v[0:1], 0, s[50:51]
	s_mov_b32 m0, s20
	v_readfirstlane_b32 s20, v200
	global_load_lds_dwordx4 v[2:3], off
	v_lshl_add_u64 v[2:3], v[0:1], 0, s[58:59]
	s_mov_b32 m0, s20
	v_readfirstlane_b32 s20, v199
	global_load_lds_dwordx4 v[2:3], off
	v_lshl_add_u64 v[0:1], v[0:1], 0, s[60:61]
	s_mov_b32 m0, s20
	s_movk_i32 s25, 0x1000
	global_load_lds_dwordx4 v[0:1], off
	s_waitcnt vmcnt(0)
.LBB0_126:
	s_waitcnt vmcnt(16)
	v_mov_b32_e32 v0, 0
	v_lshl_add_u64 v[142:143], v[138:139], 0, s[48:49]
	v_lshl_add_u64 v[144:145], v[138:139], 0, s[38:39]
	s_mov_b32 s20, 0
	s_mov_b64 s[48:49], 0
	v_mov_b32_e32 v1, v0
	v_mov_b32_e32 v2, v0
	v_mov_b32_e32 v3, v0
	v_mov_b32_e32 v4, v0
	v_mov_b32_e32 v5, v0
	v_mov_b32_e32 v6, v0
	v_mov_b32_e32 v7, v0
	v_mov_b32_e32 v8, v0
	v_mov_b32_e32 v9, v0
	v_mov_b32_e32 v10, v0
	v_mov_b32_e32 v11, v0
	v_mov_b32_e32 v12, v0
	v_mov_b32_e32 v13, v0
	v_mov_b32_e32 v14, v0
	v_mov_b32_e32 v15, v0
	v_mov_b32_e32 v16, v0
	v_mov_b32_e32 v17, v0
	v_mov_b32_e32 v18, v0
	v_mov_b32_e32 v19, v0
	v_mov_b32_e32 v20, v0
	v_mov_b32_e32 v21, v0
	v_mov_b32_e32 v22, v0
	v_mov_b32_e32 v23, v0
	v_mov_b32_e32 v24, v0
	v_mov_b32_e32 v25, v0
	v_mov_b32_e32 v26, v0
	v_mov_b32_e32 v27, v0
	v_mov_b32_e32 v28, v0
	v_mov_b32_e32 v29, v0
	v_mov_b32_e32 v30, v0
	v_mov_b32_e32 v31, v0
	v_mov_b32_e32 v64, v0
	v_mov_b32_e32 v65, v0
	v_mov_b32_e32 v66, v0
	v_mov_b32_e32 v67, v0
	v_mov_b32_e32 v68, v0
	v_mov_b32_e32 v69, v0
	v_mov_b32_e32 v70, v0
	v_mov_b32_e32 v71, v0
	v_mov_b32_e32 v72, v0
	v_mov_b32_e32 v73, v0
	v_mov_b32_e32 v74, v0
	v_mov_b32_e32 v75, v0
	v_mov_b32_e32 v76, v0
	v_mov_b32_e32 v77, v0
	v_mov_b32_e32 v78, v0
	v_mov_b32_e32 v79, v0
	v_mov_b32_e32 v80, v0
	v_mov_b32_e32 v81, v0
	v_mov_b32_e32 v82, v0
	v_mov_b32_e32 v83, v0
	v_mov_b32_e32 v84, v0
	v_mov_b32_e32 v85, v0
	v_mov_b32_e32 v86, v0
	v_mov_b32_e32 v87, v0
	v_mov_b32_e32 v88, v0
	v_mov_b32_e32 v89, v0
	v_mov_b32_e32 v90, v0
	v_mov_b32_e32 v91, v0
	v_mov_b32_e32 v92, v0
	v_mov_b32_e32 v93, v0
	v_mov_b32_e32 v94, v0
	v_mov_b32_e32 v95, v0
	v_mov_b32_e32 v32, v0
	v_mov_b32_e32 v33, v0
	v_mov_b32_e32 v34, v0
	v_mov_b32_e32 v35, v0
	v_mov_b32_e32 v36, v0
	v_mov_b32_e32 v37, v0
	v_mov_b32_e32 v38, v0
	v_mov_b32_e32 v39, v0
	v_mov_b32_e32 v40, v0
	v_mov_b32_e32 v41, v0
	v_mov_b32_e32 v42, v0
	v_mov_b32_e32 v43, v0
	v_mov_b32_e32 v44, v0
	v_mov_b32_e32 v45, v0
	v_mov_b32_e32 v46, v0
	v_mov_b32_e32 v47, v0
	v_mov_b32_e32 v48, v0
	v_mov_b32_e32 v49, v0
	v_mov_b32_e32 v50, v0
	v_mov_b32_e32 v51, v0
	v_mov_b32_e32 v52, v0
	v_mov_b32_e32 v53, v0
	v_mov_b32_e32 v54, v0
	v_mov_b32_e32 v55, v0
	v_mov_b32_e32 v56, v0
	v_mov_b32_e32 v57, v0
	v_mov_b32_e32 v58, v0
	v_mov_b32_e32 v59, v0
	v_mov_b32_e32 v60, v0
	v_mov_b32_e32 v61, v0
	v_mov_b32_e32 v62, v0
	v_mov_b32_e32 v63, v0
	v_mov_b32_e32 v96, v0
	v_mov_b32_e32 v97, v0
	v_mov_b32_e32 v98, v0
	v_mov_b32_e32 v99, v0
	v_mov_b32_e32 v100, v0
	v_mov_b32_e32 v101, v0
	v_mov_b32_e32 v102, v0
	v_mov_b32_e32 v103, v0
	v_mov_b32_e32 v104, v0
	v_mov_b32_e32 v105, v0
	v_mov_b32_e32 v106, v0
	v_mov_b32_e32 v107, v0
	v_mov_b32_e32 v108, v0
	v_mov_b32_e32 v109, v0
	v_mov_b32_e32 v110, v0
	v_mov_b32_e32 v111, v0
	v_mov_b32_e32 v112, v0
	v_mov_b32_e32 v113, v0
	v_mov_b32_e32 v114, v0
	v_mov_b32_e32 v115, v0
	v_mov_b32_e32 v116, v0
	v_mov_b32_e32 v117, v0
	v_mov_b32_e32 v118, v0
	v_mov_b32_e32 v119, v0
	v_mov_b32_e32 v120, v0
	v_mov_b32_e32 v121, v0
	v_mov_b32_e32 v122, v0
	v_mov_b32_e32 v123, v0
	v_mov_b32_e32 v124, v0
	v_mov_b32_e32 v125, v0
	v_mov_b32_e32 v126, v0
	v_mov_b32_e32 v127, v0
	s_waitcnt vmcnt(16) lgkmcnt(0)
	s_barrier
	s_branch .LBB0_128

.LBB0_172:
	s_xor_b64 s[20:21], s[34:35], -1
	s_lshl_b32 s34, s1, 8
	s_lshl_b32 s48, s0, 8
	s_ashr_i32 s35, s34, 31
	s_ashr_i32 s49, s48, 31
	s_xor_b64 s[44:45], s[46:47], -1
	s_lshl_b64 s[50:51], s[34:35], 11
	s_lshl_b64 s[52:53], s[48:49], 11
	s_andn2_b64 vcc, exec, s[20:21]
	v_add_u32_e32 v213, 0x2000, v158
	v_add_u32_e32 v212, 0x4000, v158
	v_add_u32_e32 v211, 0x6000, v158
	v_add_u32_e32 v210, 0x8000, v158
	v_add_u32_e32 v209, 0xa000, v158
	v_add_u32_e32 v208, 0xc000, v158
	v_add_u32_e32 v207, 0xe000, v158
	s_cbranch_vccnz .LBB0_174
	s_add_u32 s0, s30, s50
	s_addc_u32 s1, s31, s51
	v_lshl_add_u64 v[0:1], s[0:1], 0, v[132:133]
	v_readfirstlane_b32 s0, v158
	s_mov_b32 m0, s0
	s_mov_b64 s[38:39], 0x20000
	v_readfirstlane_b32 s0, v213
	global_load_lds_dwordx4 v[0:1], off
	v_lshl_add_u64 v[2:3], v[0:1], 0, s[38:39]
	s_mov_b32 m0, s0
	s_mov_b64 s[54:55], 0x40000
	v_readfirstlane_b32 s0, v212
	s_add_u32 s20, s42, s52
	global_load_lds_dwordx4 v[2:3], off
	v_lshl_add_u64 v[2:3], v[0:1], 0, s[54:55]
	s_mov_b32 m0, s0
	s_mov_b64 s[56:57], 0x60000
	v_readfirstlane_b32 s0, v211
	s_addc_u32 s21, s43, s53
	global_load_lds_dwordx4 v[2:3], off
	v_lshl_add_u64 v[0:1], v[0:1], 0, s[56:57]
	s_mov_b32 m0, s0
	v_readfirstlane_b32 s0, v210
	global_load_lds_dwordx4 v[0:1], off
	v_lshl_add_u64 v[0:1], s[20:21], 0, v[132:133]
	s_mov_b32 m0, s0
	v_readfirstlane_b32 s0, v209
	global_load_lds_dwordx4 v[0:1], off
	v_lshl_add_u64 v[2:3], v[0:1], 0, s[38:39]
	s_mov_b32 m0, s0
	v_readfirstlane_b32 s0, v208
	global_load_lds_dwordx4 v[2:3], off
	v_lshl_add_u64 v[2:3], v[0:1], 0, s[54:55]
	s_mov_b32 m0, s0
	v_readfirstlane_b32 s0, v207
	global_load_lds_dwordx4 v[2:3], off
	v_lshl_add_u64 v[0:1], v[0:1], 0, s[56:57]
	s_mov_b32 m0, s0
	s_nop 0
	global_load_lds_dwordx4 v[0:1], off
	s_waitcnt vmcnt(0)
.LBB0_174:
	s_waitcnt vmcnt(16)
	v_mov_b32_e32 v0, 0
	v_lshl_add_u64 v[150:151], v[138:139], 0, s[52:53]
	v_lshl_add_u64 v[152:153], v[138:139], 0, s[50:51]
	s_mov_b32 s0, 0
	s_mov_b64 s[54:55], 0
	v_mov_b32_e32 v1, v0
	v_mov_b32_e32 v2, v0
	v_mov_b32_e32 v3, v0
	v_mov_b32_e32 v4, v0
	v_mov_b32_e32 v5, v0
	v_mov_b32_e32 v6, v0
	v_mov_b32_e32 v7, v0
	v_mov_b32_e32 v8, v0
	v_mov_b32_e32 v9, v0
	v_mov_b32_e32 v10, v0
	v_mov_b32_e32 v11, v0
	v_mov_b32_e32 v12, v0
	v_mov_b32_e32 v13, v0
	v_mov_b32_e32 v14, v0
	v_mov_b32_e32 v15, v0
	v_mov_b32_e32 v16, v0
	v_mov_b32_e32 v17, v0
	v_mov_b32_e32 v18, v0
	v_mov_b32_e32 v19, v0
	v_mov_b32_e32 v20, v0
	v_mov_b32_e32 v21, v0
	v_mov_b32_e32 v22, v0
	v_mov_b32_e32 v23, v0
	v_mov_b32_e32 v24, v0
	v_mov_b32_e32 v25, v0
	v_mov_b32_e32 v26, v0
	v_mov_b32_e32 v27, v0
	v_mov_b32_e32 v28, v0
	v_mov_b32_e32 v29, v0
	v_mov_b32_e32 v30, v0
	v_mov_b32_e32 v31, v0
	v_mov_b32_e32 v64, v0
	v_mov_b32_e32 v65, v0
	v_mov_b32_e32 v66, v0
	v_mov_b32_e32 v67, v0
	v_mov_b32_e32 v68, v0
	v_mov_b32_e32 v69, v0
	v_mov_b32_e32 v70, v0
	v_mov_b32_e32 v71, v0
	v_mov_b32_e32 v72, v0
	v_mov_b32_e32 v73, v0
	v_mov_b32_e32 v74, v0
	v_mov_b32_e32 v75, v0
	v_mov_b32_e32 v76, v0
	v_mov_b32_e32 v77, v0
	v_mov_b32_e32 v78, v0
	v_mov_b32_e32 v79, v0
	v_mov_b32_e32 v80, v0
	v_mov_b32_e32 v81, v0
	v_mov_b32_e32 v82, v0
	v_mov_b32_e32 v83, v0
	v_mov_b32_e32 v84, v0
	v_mov_b32_e32 v85, v0
	v_mov_b32_e32 v86, v0
	v_mov_b32_e32 v87, v0
	v_mov_b32_e32 v88, v0
	v_mov_b32_e32 v89, v0
	v_mov_b32_e32 v90, v0
	v_mov_b32_e32 v91, v0
	v_mov_b32_e32 v92, v0
	v_mov_b32_e32 v93, v0
	v_mov_b32_e32 v94, v0
	v_mov_b32_e32 v95, v0
	v_mov_b32_e32 v32, v0
	v_mov_b32_e32 v33, v0
	v_mov_b32_e32 v34, v0
	v_mov_b32_e32 v35, v0
	v_mov_b32_e32 v36, v0
	v_mov_b32_e32 v37, v0
	v_mov_b32_e32 v38, v0
	v_mov_b32_e32 v39, v0
	v_mov_b32_e32 v40, v0
	v_mov_b32_e32 v41, v0
	v_mov_b32_e32 v42, v0
	v_mov_b32_e32 v43, v0
	v_mov_b32_e32 v44, v0
	v_mov_b32_e32 v45, v0
	v_mov_b32_e32 v46, v0
	v_mov_b32_e32 v47, v0
	v_mov_b32_e32 v48, v0
	v_mov_b32_e32 v49, v0
	v_mov_b32_e32 v50, v0
	v_mov_b32_e32 v51, v0
	v_mov_b32_e32 v52, v0
	v_mov_b32_e32 v53, v0
	v_mov_b32_e32 v54, v0
	v_mov_b32_e32 v55, v0
	v_mov_b32_e32 v56, v0
	v_mov_b32_e32 v57, v0
	v_mov_b32_e32 v58, v0
	v_mov_b32_e32 v59, v0
	v_mov_b32_e32 v60, v0
	v_mov_b32_e32 v61, v0
	v_mov_b32_e32 v62, v0
	v_mov_b32_e32 v63, v0
	v_mov_b32_e32 v96, v0
	v_mov_b32_e32 v97, v0
	v_mov_b32_e32 v98, v0
	v_mov_b32_e32 v99, v0
	v_mov_b32_e32 v100, v0
	v_mov_b32_e32 v101, v0
	v_mov_b32_e32 v102, v0
	v_mov_b32_e32 v103, v0
	v_mov_b32_e32 v104, v0
	v_mov_b32_e32 v105, v0
	v_mov_b32_e32 v106, v0
	v_mov_b32_e32 v107, v0
	v_mov_b32_e32 v108, v0
	v_mov_b32_e32 v109, v0
	v_mov_b32_e32 v110, v0
	v_mov_b32_e32 v111, v0
	v_mov_b32_e32 v112, v0
	v_mov_b32_e32 v113, v0
	v_mov_b32_e32 v114, v0
	v_mov_b32_e32 v115, v0
	v_mov_b32_e32 v116, v0
	v_mov_b32_e32 v117, v0
	v_mov_b32_e32 v118, v0
	v_mov_b32_e32 v119, v0
	v_mov_b32_e32 v120, v0
	v_mov_b32_e32 v121, v0
	v_mov_b32_e32 v122, v0
	v_mov_b32_e32 v123, v0
	v_mov_b32_e32 v124, v0
	v_mov_b32_e32 v125, v0
	v_mov_b32_e32 v126, v0
	v_mov_b32_e32 v127, v0
	s_waitcnt vmcnt(16) lgkmcnt(0)
	s_barrier
	s_branch .LBB0_176

.LBB0_185:
	s_nop 0
	v_add_u32_e32 v8, s0, v204
	v_add_u32_e32 v4, 0x10000, v8
	ds_read_b128 v[10:13], v4
	v_lshl_add_u64 v[4:5], v[0:1], 0, v[144:145]
	v_add_co_u32_e32 v6, vcc, 0x8d11000, v4
	s_mov_b32 s1, 0x31f8c000
	s_nop 0
	v_addc_co_u32_e32 v7, vcc, 0, v5, vcc
	global_load_dwordx4 v[14:17], v[6:7], off
	s_waitcnt lgkmcnt(0)
	v_lshlrev_b32_e32 v6, 16, v10
	v_and_b32_e32 v7, 0xffff0000, v10
	v_add_u32_e32 v9, 0x10480, v8
	s_addk_i32 s0, 0x1200
	v_lshl_add_u64 v[0:1], v[0:1], 0, s[50:51]
	s_cmpk_eq_i32 s0, 0x2400
	s_waitcnt vmcnt(0)
	v_lshlrev_b32_e32 v18, 16, v14
	v_and_b32_e32 v19, 0xffff0000, v14
	v_pk_mul_f32 v[6:7], v[6:7], v[18:19]
	v_lshlrev_b32_e32 v14, 16, v15
	v_cvt_pk_bf16_f32 v10, v6, v7
	v_lshlrev_b32_e32 v6, 16, v11
	v_and_b32_e32 v7, 0xffff0000, v11
	v_and_b32_e32 v15, 0xffff0000, v15
	v_pk_mul_f32 v[6:7], v[6:7], v[14:15]
	v_lshlrev_b32_e32 v14, 16, v16
	v_cvt_pk_bf16_f32 v11, v6, v7
	v_lshlrev_b32_e32 v6, 16, v12
	v_and_b32_e32 v7, 0xffff0000, v12
	v_and_b32_e32 v15, 0xffff0000, v16
	v_pk_mul_f32 v[6:7], v[6:7], v[14:15]
	v_lshlrev_b32_e32 v14, 16, v17
	v_cvt_pk_bf16_f32 v12, v6, v7
	v_lshlrev_b32_e32 v6, 16, v13
	v_and_b32_e32 v7, 0xffff0000, v13
	v_and_b32_e32 v15, 0xffff0000, v17
	v_pk_mul_f32 v[6:7], v[6:7], v[14:15]
	s_nop 0
	v_cvt_pk_bf16_f32 v13, v6, v7
	v_lshl_add_u64 v[6:7], v[2:3], 0, v[144:145]
	v_add_co_u32_e32 v14, vcc, s1, v6
	v_lshl_add_u64 v[2:3], v[2:3], 0, s[48:49]
	s_nop 0
	v_addc_co_u32_e32 v15, vcc, 0, v7, vcc
	global_store_dwordx4 v[14:15], v[10:13], off
	v_add_co_u32_e32 v14, vcc, s20, v4
	ds_read_b128 v[10:13], v9
	s_nop 0
	v_addc_co_u32_e32 v15, vcc, 0, v5, vcc
	global_load_dwordx4 v[14:17], v[14:15], off
	v_add_u32_e32 v9, 0x10900, v8
	s_waitcnt lgkmcnt(0)
	v_lshlrev_b32_e32 v18, 16, v10
	v_and_b32_e32 v19, 0xffff0000, v10
	v_add_u32_e32 v8, 0x10d80, v8
	s_waitcnt vmcnt(0)
	v_lshlrev_b32_e32 v20, 16, v14
	v_and_b32_e32 v21, 0xffff0000, v14
	v_pk_mul_f32 v[18:19], v[18:19], v[20:21]
	v_lshlrev_b32_e32 v14, 16, v15
	v_cvt_pk_bf16_f32 v10, v18, v19
	v_lshlrev_b32_e32 v18, 16, v11
	v_and_b32_e32 v19, 0xffff0000, v11
	v_and_b32_e32 v15, 0xffff0000, v15
	v_pk_mul_f32 v[14:15], v[18:19], v[14:15]
	v_lshlrev_b32_e32 v18, 16, v16
	v_cvt_pk_bf16_f32 v11, v14, v15
	v_lshlrev_b32_e32 v14, 16, v12
	v_and_b32_e32 v15, 0xffff0000, v12
	v_and_b32_e32 v19, 0xffff0000, v16
	v_pk_mul_f32 v[14:15], v[14:15], v[18:19]
	v_lshlrev_b32_e32 v16, 16, v17
	v_cvt_pk_bf16_f32 v12, v14, v15
	v_lshlrev_b32_e32 v14, 16, v13
	v_and_b32_e32 v15, 0xffff0000, v13
	v_and_b32_e32 v17, 0xffff0000, v17
	v_pk_mul_f32 v[14:15], v[14:15], v[16:17]
	s_nop 0
	v_cvt_pk_bf16_f32 v13, v14, v15
	v_add_co_u32_e32 v14, vcc, s21, v6
	s_nop 1
	v_addc_co_u32_e32 v15, vcc, 0, v7, vcc
	global_store_dwordx4 v[14:15], v[10:13], off
	v_add_co_u32_e32 v14, vcc, s34, v4
	ds_read_b128 v[10:13], v9
	s_nop 0
	v_addc_co_u32_e32 v15, vcc, 0, v5, vcc
	global_load_dwordx4 v[14:17], v[14:15], off
	s_waitcnt lgkmcnt(0)
	v_lshlrev_b32_e32 v18, 16, v10
	v_and_b32_e32 v19, 0xffff0000, v10
	s_waitcnt vmcnt(0)
	v_lshlrev_b32_e32 v20, 16, v14
	v_and_b32_e32 v21, 0xffff0000, v14
	v_pk_mul_f32 v[18:19], v[18:19], v[20:21]
	v_lshlrev_b32_e32 v14, 16, v15
	v_cvt_pk_bf16_f32 v10, v18, v19
	v_lshlrev_b32_e32 v18, 16, v11
	v_and_b32_e32 v19, 0xffff0000, v11
	v_and_b32_e32 v15, 0xffff0000, v15
	v_pk_mul_f32 v[14:15], v[18:19], v[14:15]
	v_lshlrev_b32_e32 v18, 16, v16
	v_cvt_pk_bf16_f32 v11, v14, v15
	v_lshlrev_b32_e32 v14, 16, v12
	v_and_b32_e32 v15, 0xffff0000, v12
	v_and_b32_e32 v19, 0xffff0000, v16
	v_pk_mul_f32 v[14:15], v[14:15], v[18:19]
	v_lshlrev_b32_e32 v16, 16, v17
	v_cvt_pk_bf16_f32 v12, v14, v15
	v_lshlrev_b32_e32 v14, 16, v13
	v_and_b32_e32 v15, 0xffff0000, v13
	v_and_b32_e32 v17, 0xffff0000, v17
	v_pk_mul_f32 v[14:15], v[14:15], v[16:17]
	s_nop 0
	v_cvt_pk_bf16_f32 v13, v14, v15
	v_add_co_u32_e32 v14, vcc, s35, v6
	s_nop 1
	v_addc_co_u32_e32 v15, vcc, 0, v7, vcc
	v_add_co_u32_e32 v4, vcc, s38, v4
	global_store_dwordx4 v[14:15], v[10:13], off
	s_nop 0
	v_addc_co_u32_e32 v5, vcc, 0, v5, vcc
	global_load_dwordx4 v[12:15], v[4:5], off
	ds_read_b128 v[8:11], v8
	s_waitcnt lgkmcnt(0)
	v_lshlrev_b32_e32 v4, 16, v8
	v_and_b32_e32 v5, 0xffff0000, v8
	s_waitcnt vmcnt(0)
	v_lshlrev_b32_e32 v16, 16, v12
	v_and_b32_e32 v17, 0xffff0000, v12
	v_pk_mul_f32 v[4:5], v[4:5], v[16:17]
	v_lshlrev_b32_e32 v12, 16, v13
	v_cvt_pk_bf16_f32 v8, v4, v5
	v_lshlrev_b32_e32 v4, 16, v9
	v_and_b32_e32 v5, 0xffff0000, v9
	v_and_b32_e32 v13, 0xffff0000, v13
	v_pk_mul_f32 v[4:5], v[4:5], v[12:13]
	v_lshlrev_b32_e32 v12, 16, v14
	v_cvt_pk_bf16_f32 v9, v4, v5
	v_lshlrev_b32_e32 v4, 16, v10
	v_and_b32_e32 v5, 0xffff0000, v10
	v_and_b32_e32 v13, 0xffff0000, v14
	v_pk_mul_f32 v[4:5], v[4:5], v[12:13]
	v_lshlrev_b32_e32 v12, 16, v15
	v_cvt_pk_bf16_f32 v10, v4, v5
	v_lshlrev_b32_e32 v4, 16, v11
	v_and_b32_e32 v5, 0xffff0000, v11
	v_and_b32_e32 v13, 0xffff0000, v15
	v_pk_mul_f32 v[4:5], v[4:5], v[12:13]
	s_nop 0
	v_cvt_pk_bf16_f32 v11, v4, v5
	v_add_co_u32_e32 v4, vcc, 0x31f98000, v6
	s_nop 1
	v_addc_co_u32_e32 v5, vcc, 0, v7, vcc
	global_store_dwordx4 v[4:5], v[8:11], off
	s_cbranch_scc0 .LBB0_185
	s_waitcnt vmcnt(16)
	v_mov_b32_e32 v0, 0
	s_mov_b32 s0, 0
	s_mov_b64 s[34:35], 0
	v_mov_b32_e32 v1, v0
	v_mov_b32_e32 v2, v0
	v_mov_b32_e32 v3, v0
	v_mov_b32_e32 v4, v0
	v_mov_b32_e32 v5, v0
	v_mov_b32_e32 v6, v0
	v_mov_b32_e32 v7, v0
	v_mov_b32_e32 v8, v0
	v_mov_b32_e32 v9, v0
	v_mov_b32_e32 v10, v0
	v_mov_b32_e32 v11, v0
	v_mov_b32_e32 v12, v0
	v_mov_b32_e32 v13, v0
	v_mov_b32_e32 v14, v0
	v_mov_b32_e32 v15, v0
	v_mov_b32_e32 v16, v0
	v_mov_b32_e32 v17, v0
	v_mov_b32_e32 v18, v0
	v_mov_b32_e32 v19, v0
	v_mov_b32_e32 v20, v0
	v_mov_b32_e32 v21, v0
	v_mov_b32_e32 v22, v0
	v_mov_b32_e32 v23, v0
	v_mov_b32_e32 v24, v0
	v_mov_b32_e32 v25, v0
	v_mov_b32_e32 v26, v0
	v_mov_b32_e32 v27, v0
	v_mov_b32_e32 v28, v0
	v_mov_b32_e32 v29, v0
	v_mov_b32_e32 v30, v0
	v_mov_b32_e32 v31, v0
	v_mov_b32_e32 v64, v0
	v_mov_b32_e32 v65, v0
	v_mov_b32_e32 v66, v0
	v_mov_b32_e32 v67, v0
	v_mov_b32_e32 v68, v0
	v_mov_b32_e32 v69, v0
	v_mov_b32_e32 v70, v0
	v_mov_b32_e32 v71, v0
	v_mov_b32_e32 v72, v0
	v_mov_b32_e32 v73, v0
	v_mov_b32_e32 v74, v0
	v_mov_b32_e32 v75, v0
	v_mov_b32_e32 v76, v0
	v_mov_b32_e32 v77, v0
	v_mov_b32_e32 v78, v0
	v_mov_b32_e32 v79, v0
	v_mov_b32_e32 v80, v0
	v_mov_b32_e32 v81, v0
	v_mov_b32_e32 v82, v0
	v_mov_b32_e32 v83, v0
	v_mov_b32_e32 v84, v0
	v_mov_b32_e32 v85, v0
	v_mov_b32_e32 v86, v0
	v_mov_b32_e32 v87, v0
	v_mov_b32_e32 v88, v0
	v_mov_b32_e32 v89, v0
	v_mov_b32_e32 v90, v0
	v_mov_b32_e32 v91, v0
	v_mov_b32_e32 v92, v0
	v_mov_b32_e32 v93, v0
	v_mov_b32_e32 v94, v0
	v_mov_b32_e32 v95, v0
	v_mov_b32_e32 v32, v0
	v_mov_b32_e32 v33, v0
	v_mov_b32_e32 v34, v0
	v_mov_b32_e32 v35, v0
	v_mov_b32_e32 v36, v0
	v_mov_b32_e32 v37, v0
	v_mov_b32_e32 v38, v0
	v_mov_b32_e32 v39, v0
	v_mov_b32_e32 v40, v0
	v_mov_b32_e32 v41, v0
	v_mov_b32_e32 v42, v0
	v_mov_b32_e32 v43, v0
	v_mov_b32_e32 v44, v0
	v_mov_b32_e32 v45, v0
	v_mov_b32_e32 v46, v0
	v_mov_b32_e32 v47, v0
	v_mov_b32_e32 v48, v0
	v_mov_b32_e32 v49, v0
	v_mov_b32_e32 v50, v0
	v_mov_b32_e32 v51, v0
	v_mov_b32_e32 v52, v0
	v_mov_b32_e32 v53, v0
	v_mov_b32_e32 v54, v0
	v_mov_b32_e32 v55, v0
	v_mov_b32_e32 v56, v0
	v_mov_b32_e32 v57, v0
	v_mov_b32_e32 v58, v0
	v_mov_b32_e32 v59, v0
	v_mov_b32_e32 v60, v0
	v_mov_b32_e32 v61, v0
	v_mov_b32_e32 v62, v0
	v_mov_b32_e32 v63, v0
	v_mov_b32_e32 v96, v0
	v_mov_b32_e32 v97, v0
	v_mov_b32_e32 v98, v0
	v_mov_b32_e32 v99, v0
	v_mov_b32_e32 v100, v0
	v_mov_b32_e32 v101, v0
	v_mov_b32_e32 v102, v0
	v_mov_b32_e32 v103, v0
	v_mov_b32_e32 v104, v0
	v_mov_b32_e32 v105, v0
	v_mov_b32_e32 v106, v0
	v_mov_b32_e32 v107, v0
	v_mov_b32_e32 v108, v0
	v_mov_b32_e32 v109, v0
	v_mov_b32_e32 v110, v0
	v_mov_b32_e32 v111, v0
	v_mov_b32_e32 v112, v0
	v_mov_b32_e32 v113, v0
	v_mov_b32_e32 v114, v0
	v_mov_b32_e32 v115, v0
	v_mov_b32_e32 v116, v0
	v_mov_b32_e32 v117, v0
	v_mov_b32_e32 v118, v0
	v_mov_b32_e32 v119, v0
	v_mov_b32_e32 v120, v0
	v_mov_b32_e32 v121, v0
	v_mov_b32_e32 v122, v0
	v_mov_b32_e32 v123, v0
	v_mov_b32_e32 v124, v0
	v_mov_b32_e32 v125, v0
	v_mov_b32_e32 v126, v0
	v_mov_b32_e32 v127, v0
	s_barrier
	s_branch .LBB0_188

.LBB0_328:
	s_xor_b64 s[20:21], s[34:35], -1
	s_lshl_b32 s34, s1, 8
	s_lshl_b32 s46, s0, 8
	s_ashr_i32 s35, s34, 31
	s_ashr_i32 s47, s46, 31
	s_xor_b64 s[44:45], s[48:49], -1
	s_lshl_b64 s[38:39], s[34:35], 11
	s_lshl_b64 s[50:51], s[46:47], 11
	s_andn2_b64 vcc, exec, s[20:21]
	v_add_u32_e32 v209, 0x2000, v154
	v_add_u32_e32 v208, 0x4000, v154
	v_add_u32_e32 v207, 0x6000, v154
	v_add_u32_e32 v206, 0x8000, v154
	v_add_u32_e32 v205, 0xa000, v154
	v_add_u32_e32 v204, 0xc000, v154
	v_add_u32_e32 v203, 0xe000, v154
	s_cbranch_vccnz .LBB0_330
	s_add_u32 s0, s40, s38
	s_addc_u32 s1, s41, s39
	v_lshl_add_u64 v[0:1], s[0:1], 0, v[128:129]
	v_readfirstlane_b32 s0, v154
	s_mov_b32 m0, s0
	s_mov_b64 s[52:53], 0x20000
	v_readfirstlane_b32 s0, v209
	global_load_lds_dwordx4 v[0:1], off
	v_lshl_add_u64 v[2:3], v[0:1], 0, s[52:53]
	s_mov_b32 m0, s0
	s_mov_b64 s[58:59], 0x40000
	v_readfirstlane_b32 s0, v208
	s_add_u32 s20, s42, s50
	global_load_lds_dwordx4 v[2:3], off
	v_lshl_add_u64 v[2:3], v[0:1], 0, s[58:59]
	s_mov_b32 m0, s0
	s_mov_b64 s[60:61], 0x60000
	v_readfirstlane_b32 s0, v207
	s_addc_u32 s21, s43, s51
	global_load_lds_dwordx4 v[2:3], off
	v_lshl_add_u64 v[0:1], v[0:1], 0, s[60:61]
	s_mov_b32 m0, s0
	v_readfirstlane_b32 s0, v206
	global_load_lds_dwordx4 v[0:1], off
	v_lshl_add_u64 v[0:1], s[20:21], 0, v[128:129]
	s_mov_b32 m0, s0
	v_readfirstlane_b32 s0, v205
	global_load_lds_dwordx4 v[0:1], off
	v_lshl_add_u64 v[2:3], v[0:1], 0, s[52:53]
	s_mov_b32 m0, s0
	v_readfirstlane_b32 s0, v204
	global_load_lds_dwordx4 v[2:3], off
	v_lshl_add_u64 v[2:3], v[0:1], 0, s[58:59]
	s_mov_b32 m0, s0
	v_readfirstlane_b32 s0, v203
	global_load_lds_dwordx4 v[2:3], off
	v_lshl_add_u64 v[0:1], v[0:1], 0, s[60:61]
	s_mov_b32 m0, s0
	s_nop 0
	global_load_lds_dwordx4 v[0:1], off
	s_waitcnt vmcnt(0)
.LBB0_330:
	s_waitcnt vmcnt(16)
	v_mov_b32_e32 v0, 0
	v_lshl_add_u64 v[146:147], v[140:141], 0, s[50:51]
	v_lshl_add_u64 v[148:149], v[140:141], 0, s[38:39]
	s_mov_b32 s0, 0
	s_mov_b64 s[50:51], 0
	v_mov_b32_e32 v1, v0
	v_mov_b32_e32 v2, v0
	v_mov_b32_e32 v3, v0
	v_mov_b32_e32 v4, v0
	v_mov_b32_e32 v5, v0
	v_mov_b32_e32 v6, v0
	v_mov_b32_e32 v7, v0
	v_mov_b32_e32 v8, v0
	v_mov_b32_e32 v9, v0
	v_mov_b32_e32 v10, v0
	v_mov_b32_e32 v11, v0
	v_mov_b32_e32 v12, v0
	v_mov_b32_e32 v13, v0
	v_mov_b32_e32 v14, v0
	v_mov_b32_e32 v15, v0
	v_mov_b32_e32 v16, v0
	v_mov_b32_e32 v17, v0
	v_mov_b32_e32 v18, v0
	v_mov_b32_e32 v19, v0
	v_mov_b32_e32 v20, v0
	v_mov_b32_e32 v21, v0
	v_mov_b32_e32 v22, v0
	v_mov_b32_e32 v23, v0
	v_mov_b32_e32 v24, v0
	v_mov_b32_e32 v25, v0
	v_mov_b32_e32 v26, v0
	v_mov_b32_e32 v27, v0
	v_mov_b32_e32 v28, v0
	v_mov_b32_e32 v29, v0
	v_mov_b32_e32 v30, v0
	v_mov_b32_e32 v31, v0
	v_mov_b32_e32 v64, v0
	v_mov_b32_e32 v65, v0
	v_mov_b32_e32 v66, v0
	v_mov_b32_e32 v67, v0
	v_mov_b32_e32 v68, v0
	v_mov_b32_e32 v69, v0
	v_mov_b32_e32 v70, v0
	v_mov_b32_e32 v71, v0
	v_mov_b32_e32 v72, v0
	v_mov_b32_e32 v73, v0
	v_mov_b32_e32 v74, v0
	v_mov_b32_e32 v75, v0
	v_mov_b32_e32 v76, v0
	v_mov_b32_e32 v77, v0
	v_mov_b32_e32 v78, v0
	v_mov_b32_e32 v79, v0
	v_mov_b32_e32 v80, v0
	v_mov_b32_e32 v81, v0
	v_mov_b32_e32 v82, v0
	v_mov_b32_e32 v83, v0
	v_mov_b32_e32 v84, v0
	v_mov_b32_e32 v85, v0
	v_mov_b32_e32 v86, v0
	v_mov_b32_e32 v87, v0
	v_mov_b32_e32 v88, v0
	v_mov_b32_e32 v89, v0
	v_mov_b32_e32 v90, v0
	v_mov_b32_e32 v91, v0
	v_mov_b32_e32 v92, v0
	v_mov_b32_e32 v93, v0
	v_mov_b32_e32 v94, v0
	v_mov_b32_e32 v95, v0
	v_mov_b32_e32 v32, v0
	v_mov_b32_e32 v33, v0
	v_mov_b32_e32 v34, v0
	v_mov_b32_e32 v35, v0
	v_mov_b32_e32 v36, v0
	v_mov_b32_e32 v37, v0
	v_mov_b32_e32 v38, v0
	v_mov_b32_e32 v39, v0
	v_mov_b32_e32 v40, v0
	v_mov_b32_e32 v41, v0
	v_mov_b32_e32 v42, v0
	v_mov_b32_e32 v43, v0
	v_mov_b32_e32 v44, v0
	v_mov_b32_e32 v45, v0
	v_mov_b32_e32 v46, v0
	v_mov_b32_e32 v47, v0
	v_mov_b32_e32 v48, v0
	v_mov_b32_e32 v49, v0
	v_mov_b32_e32 v50, v0
	v_mov_b32_e32 v51, v0
	v_mov_b32_e32 v52, v0
	v_mov_b32_e32 v53, v0
	v_mov_b32_e32 v54, v0
	v_mov_b32_e32 v55, v0
	v_mov_b32_e32 v56, v0
	v_mov_b32_e32 v57, v0
	v_mov_b32_e32 v58, v0
	v_mov_b32_e32 v59, v0
	v_mov_b32_e32 v60, v0
	v_mov_b32_e32 v61, v0
	v_mov_b32_e32 v62, v0
	v_mov_b32_e32 v63, v0
	v_mov_b32_e32 v96, v0
	v_mov_b32_e32 v97, v0
	v_mov_b32_e32 v98, v0
	v_mov_b32_e32 v99, v0
	v_mov_b32_e32 v100, v0
	v_mov_b32_e32 v101, v0
	v_mov_b32_e32 v102, v0
	v_mov_b32_e32 v103, v0
	v_mov_b32_e32 v104, v0
	v_mov_b32_e32 v105, v0
	v_mov_b32_e32 v106, v0
	v_mov_b32_e32 v107, v0
	v_mov_b32_e32 v108, v0
	v_mov_b32_e32 v109, v0
	v_mov_b32_e32 v110, v0
	v_mov_b32_e32 v111, v0
	v_mov_b32_e32 v112, v0
	v_mov_b32_e32 v113, v0
	v_mov_b32_e32 v114, v0
	v_mov_b32_e32 v115, v0
	v_mov_b32_e32 v116, v0
	v_mov_b32_e32 v117, v0
	v_mov_b32_e32 v118, v0
	v_mov_b32_e32 v119, v0
	v_mov_b32_e32 v120, v0
	v_mov_b32_e32 v121, v0
	v_mov_b32_e32 v122, v0
	v_mov_b32_e32 v123, v0
	v_mov_b32_e32 v124, v0
	v_mov_b32_e32 v125, v0
	v_mov_b32_e32 v126, v0
	v_mov_b32_e32 v127, v0
	s_waitcnt vmcnt(16) lgkmcnt(0)
	s_barrier
	s_branch .LBB0_332

.LBB0_370:
	s_xor_b64 s[20:21], s[34:35], -1
	s_lshl_b32 s52, s1, 8
	s_lshl_b32 s34, s0, 8
	s_ashr_i32 s53, s52, 31
	s_ashr_i32 s35, s34, 31
	s_xor_b64 s[50:51], s[30:31], -1
	s_lshl_b64 s[38:39], s[52:53], 11
	s_lshl_b64 s[40:41], s[34:35], 11
	s_andn2_b64 vcc, exec, s[20:21]
	v_add_u32_e32 v217, 0x2000, v156
	v_add_u32_e32 v216, 0x4000, v156
	v_add_u32_e32 v215, 0x6000, v156
	v_add_u32_e32 v155, 0x8000, v156
	v_add_u32_e32 v154, 0xa000, v156
	v_add_u32_e32 v149, 0xc000, v156
	v_add_u32_e32 v132, 0xe000, v156
	s_cbranch_vccnz .LBB0_372
	s_add_u32 s0, s48, s38
	s_addc_u32 s1, s49, s39
	v_lshl_add_u64 v[0:1], s[0:1], 0, v[138:139]
	v_readfirstlane_b32 s0, v156
	s_mov_b32 m0, s0
	s_mov_b64 s[42:43], 0x20000
	v_readfirstlane_b32 s0, v217
	global_load_lds_dwordx4 v[0:1], off
	v_lshl_add_u64 v[2:3], v[0:1], 0, s[42:43]
	s_mov_b32 m0, s0
	s_mov_b64 s[54:55], 0x40000
	v_readfirstlane_b32 s0, v216
	s_add_u32 s20, s44, s40
	global_load_lds_dwordx4 v[2:3], off
	v_lshl_add_u64 v[2:3], v[0:1], 0, s[54:55]
	s_mov_b32 m0, s0
	s_mov_b64 s[56:57], 0x60000
	v_readfirstlane_b32 s0, v215
	s_addc_u32 s21, s45, s41
	global_load_lds_dwordx4 v[2:3], off
	v_lshl_add_u64 v[0:1], v[0:1], 0, s[56:57]
	s_mov_b32 m0, s0
	v_readfirstlane_b32 s0, v155
	global_load_lds_dwordx4 v[0:1], off
	v_lshl_add_u64 v[0:1], s[20:21], 0, v[138:139]
	s_mov_b32 m0, s0
	v_readfirstlane_b32 s0, v154
	global_load_lds_dwordx4 v[0:1], off
	v_lshl_add_u64 v[2:3], v[0:1], 0, s[42:43]
	s_mov_b32 m0, s0
	v_readfirstlane_b32 s0, v149
	global_load_lds_dwordx4 v[2:3], off
	v_lshl_add_u64 v[2:3], v[0:1], 0, s[54:55]
	s_mov_b32 m0, s0
	v_readfirstlane_b32 s0, v132
	global_load_lds_dwordx4 v[2:3], off
	v_lshl_add_u64 v[0:1], v[0:1], 0, s[56:57]
	s_mov_b32 m0, s0
	s_nop 0
	global_load_lds_dwordx4 v[0:1], off
	s_waitcnt vmcnt(0)
.LBB0_372:
	s_waitcnt vmcnt(16)
	v_mov_b32_e32 v0, 0
	v_lshl_add_u64 v[128:129], v[142:143], 0, s[40:41]
	v_lshl_add_u64 v[130:131], v[142:143], 0, s[38:39]
	s_mov_b32 s0, 0
	s_mov_b64 s[40:41], 0
	v_mov_b32_e32 v1, v0
	v_mov_b32_e32 v2, v0
	v_mov_b32_e32 v3, v0
	v_mov_b32_e32 v4, v0
	v_mov_b32_e32 v5, v0
	v_mov_b32_e32 v6, v0
	v_mov_b32_e32 v7, v0
	v_mov_b32_e32 v8, v0
	v_mov_b32_e32 v9, v0
	v_mov_b32_e32 v10, v0
	v_mov_b32_e32 v11, v0
	v_mov_b32_e32 v12, v0
	v_mov_b32_e32 v13, v0
	v_mov_b32_e32 v14, v0
	v_mov_b32_e32 v15, v0
	v_mov_b32_e32 v16, v0
	v_mov_b32_e32 v17, v0
	v_mov_b32_e32 v18, v0
	v_mov_b32_e32 v19, v0
	v_mov_b32_e32 v20, v0
	v_mov_b32_e32 v21, v0
	v_mov_b32_e32 v22, v0
	v_mov_b32_e32 v23, v0
	v_mov_b32_e32 v24, v0
	v_mov_b32_e32 v25, v0
	v_mov_b32_e32 v26, v0
	v_mov_b32_e32 v27, v0
	v_mov_b32_e32 v28, v0
	v_mov_b32_e32 v29, v0
	v_mov_b32_e32 v30, v0
	v_mov_b32_e32 v31, v0
	v_mov_b32_e32 v64, v0
	v_mov_b32_e32 v65, v0
	v_mov_b32_e32 v66, v0
	v_mov_b32_e32 v67, v0
	v_mov_b32_e32 v68, v0
	v_mov_b32_e32 v69, v0
	v_mov_b32_e32 v70, v0
	v_mov_b32_e32 v71, v0
	v_mov_b32_e32 v72, v0
	v_mov_b32_e32 v73, v0
	v_mov_b32_e32 v74, v0
	v_mov_b32_e32 v75, v0
	v_mov_b32_e32 v76, v0
	v_mov_b32_e32 v77, v0
	v_mov_b32_e32 v78, v0
	v_mov_b32_e32 v79, v0
	v_mov_b32_e32 v80, v0
	v_mov_b32_e32 v81, v0
	v_mov_b32_e32 v82, v0
	v_mov_b32_e32 v83, v0
	v_mov_b32_e32 v84, v0
	v_mov_b32_e32 v85, v0
	v_mov_b32_e32 v86, v0
	v_mov_b32_e32 v87, v0
	v_mov_b32_e32 v88, v0
	v_mov_b32_e32 v89, v0
	v_mov_b32_e32 v90, v0
	v_mov_b32_e32 v91, v0
	v_mov_b32_e32 v92, v0
	v_mov_b32_e32 v93, v0
	v_mov_b32_e32 v94, v0
	v_mov_b32_e32 v95, v0
	v_mov_b32_e32 v32, v0
	v_mov_b32_e32 v33, v0
	v_mov_b32_e32 v34, v0
	v_mov_b32_e32 v35, v0
	v_mov_b32_e32 v36, v0
	v_mov_b32_e32 v37, v0
	v_mov_b32_e32 v38, v0
	v_mov_b32_e32 v39, v0
	v_mov_b32_e32 v40, v0
	v_mov_b32_e32 v41, v0
	v_mov_b32_e32 v42, v0
	v_mov_b32_e32 v43, v0
	v_mov_b32_e32 v44, v0
	v_mov_b32_e32 v45, v0
	v_mov_b32_e32 v46, v0
	v_mov_b32_e32 v47, v0
	v_mov_b32_e32 v48, v0
	v_mov_b32_e32 v49, v0
	v_mov_b32_e32 v50, v0
	v_mov_b32_e32 v51, v0
	v_mov_b32_e32 v52, v0
	v_mov_b32_e32 v53, v0
	v_mov_b32_e32 v54, v0
	v_mov_b32_e32 v55, v0
	v_mov_b32_e32 v56, v0
	v_mov_b32_e32 v57, v0
	v_mov_b32_e32 v58, v0
	v_mov_b32_e32 v59, v0
	v_mov_b32_e32 v60, v0
	v_mov_b32_e32 v61, v0
	v_mov_b32_e32 v62, v0
	v_mov_b32_e32 v63, v0
	v_mov_b32_e32 v96, v0
	v_mov_b32_e32 v97, v0
	v_mov_b32_e32 v98, v0
	v_mov_b32_e32 v99, v0
	v_mov_b32_e32 v100, v0
	v_mov_b32_e32 v101, v0
	v_mov_b32_e32 v102, v0
	v_mov_b32_e32 v103, v0
	v_mov_b32_e32 v104, v0
	v_mov_b32_e32 v105, v0
	v_mov_b32_e32 v106, v0
	v_mov_b32_e32 v107, v0
	v_mov_b32_e32 v108, v0
	v_mov_b32_e32 v109, v0
	v_mov_b32_e32 v110, v0
	v_mov_b32_e32 v111, v0
	v_mov_b32_e32 v112, v0
	v_mov_b32_e32 v113, v0
	v_mov_b32_e32 v114, v0
	v_mov_b32_e32 v115, v0
	v_mov_b32_e32 v116, v0
	v_mov_b32_e32 v117, v0
	v_mov_b32_e32 v118, v0
	v_mov_b32_e32 v119, v0
	v_mov_b32_e32 v120, v0
	v_mov_b32_e32 v121, v0
	v_mov_b32_e32 v122, v0
	v_mov_b32_e32 v123, v0
	v_mov_b32_e32 v124, v0
	v_mov_b32_e32 v125, v0
	v_mov_b32_e32 v126, v0
	v_mov_b32_e32 v127, v0
	s_waitcnt vmcnt(16) lgkmcnt(0)
	s_barrier
	s_branch .LBB0_374
